# attention phase: one static s_setprio 1 for waves 4-7 (younger half), reset at phase end
# baseline (speedup 1.0000x reference)
; #define LAS __attribute__((address_space(3)))
; template <bool MOBA>
; __device__ __forceinline__ void attn_unit(unsigned char* lds, LAS unsigned char* lds3, const Params& p, int b, int h, int qb) {
;     int tid_ = threadIdx.x; asm volatile("" : "+v"(tid_)); const int tid = tid_, lane = tid & 63, w = __builtin_amdgcn_readfirstlane(tid >> 6), fr = lane & 15, fq = lane >> 4;
;     const bf16_t* Qg = (const bf16_t*)(p.ws + WS_R1); const bf16_t* Kg = Qg + (size_t)MROWS * DM; const bf16_t* Vg = Kg + (size_t)MROWS * DM;
;     bf16_t* Og = (bf16_t*)(p.ws + WS_R2);
;     const int hcol = (MOBA ? 8 + h : h) * 64; const size_t rowbase = (size_t)b * SEQ;
;     LAS bf16_t* Ks = (LAS bf16_t*)lds3; LAS bf16_t* Vt = (LAS bf16_t*)(lds3 + 36864);
;     LAS float* Fs = (LAS float*)(lds3 + 73728); LAS float* kms = Fs; LAS float* tbl = (LAS float*)(lds3 + 73728 + 4096); LAS unsigned* sel = (LAS unsigned*)(lds3 + 73728 + 4096 + 512);
; __device__ __forceinline__ void phase_attn(const Params& p, unsigned char* lds, LAS unsigned char* lds3) {
;     for (int u = blockIdx.x; u < 2048; u += gridDim.x) {
;         const int bx = u & 255, i = u >> 8; const int wv = (bx & 7) * 32 + (bx >> 3);
;         const int combo = wv >> 2, quarter = wv & 3; const int k = i & 3;
;         const int b = combo >> 3, h = ((combo & 7) + 2 * k + (i >> 2)) & 7;
;         const int qb = (k == 0) ? quarter : (k == 1) ? 15 - quarter : (k == 2) ? 7 - quarter : 8 + quarter;
;         if (i < 4) attn_unit<false>(lds, lds3, p, b, h, qb); else attn_unit<true>(lds, lds3, p, b, h, qb);
.LBB0_356:
	s_andn2_b64 vcc, exec, s[0:1]
	s_cbranch_vccnz .LBB0_617
	v_readfirstlane_b32 s100, v174
	s_nop 3
	s_cmp_ge_u32 s100, 0x100
	s_cbranch_scc0 .Lattn_noprio
	s_setprio 1
.Lattn_noprio:
	v_writelane_b32 v255, s3, 15
	s_load_dwordx2 s[2:3], s[86:87], 0x90
	v_writelane_b32 v255, s90, 16
	v_writelane_b32 v255, s69, 17
	v_writelane_b32 v255, s68, 18
	s_waitcnt lgkmcnt(0)
	v_writelane_b32 v255, s2, 19
	s_nop 1
	v_writelane_b32 v255, s3, 20
	v_readlane_b32 s2, v254, 11
	v_readlane_b32 s3, v254, 12
	s_andn2_b64 vcc, exec, s[2:3]
	s_cbranch_vccnz .LBB0_555
	v_readlane_b32 s2, v255, 19
	v_readlane_b32 s3, v255, 20
	s_add_u32 s4, s2, 0x13d00000
	s_addc_u32 s5, s3, 0
	s_add_u32 s50, s2, 0x17d00000
	s_addc_u32 s51, s3, 0
	s_add_u32 s52, s2, 0xfd00000
	v_writelane_b32 v255, s4, 21
	s_addc_u32 s53, s3, 0
	s_load_dwordx2 s[0:1], s[86:87], 0x60
	v_writelane_b32 v255, s5, 22
	s_add_u32 s4, s2, 0x64c0000
	v_writelane_b32 v255, s4, 23
	s_addc_u32 s4, s3, 0
	v_writelane_b32 v255, s4, 24
	s_add_u32 s4, s2, 0x6400000
	v_writelane_b32 v255, s4, 25
	s_addc_u32 s4, s3, 0
	s_add_u32 s80, s2, 0xa500000
	s_addc_u32 s81, s3, 0
	v_writelane_b32 v255, s4, 26
	s_add_u32 s4, s2, 0x6300000
	v_writelane_b32 v255, s4, 27
	s_addc_u32 s4, s3, 0
	s_add_u32 s2, s2, 0x13cc0400
	v_writelane_b32 v255, s4, 28
	s_addc_u32 s3, s3, 0
	v_writelane_b32 v255, s2, 29
	s_mov_b32 s95, s73
	s_nop 0
	v_writelane_b32 v255, s3, 30
	v_writelane_b32 v255, s88, 31
	s_mov_b32 s2, s73
	s_nop 0
	v_writelane_b32 v255, s89, 32
	v_writelane_b32 v255, s52, 33
	s_nop 1
	v_writelane_b32 v255, s53, 34
	v_writelane_b32 v255, s50, 35
	s_nop 1
	v_writelane_b32 v255, s51, 36
	s_branch .LBB0_361

; __device__ __forceinline__ unsigned xb_add(unsigned* p, unsigned v) { return __hip_atomic_fetch_add(p, v, __ATOMIC_RELAXED, __HIP_MEMORY_SCOPE_AGENT); }
; __device__ __forceinline__ void xcd_barrier(const XcdBarrier& b) {
;     asm volatile("s_waitcnt vmcnt(0)" ::: "memory");
;     __syncthreads();
;     if (threadIdx.x == 0) {
;         unsigned* bar = b.bar;
;         __builtin_amdgcn_s_waitcnt(0);
;         unsigned nloc = b.st[0], nx = b.st[1];
;         if (nloc == 0u) { xcd_barrier_complete(bar, b.x, nloc, nx); b.st[0] = nloc; b.st[1] = nx; }
;         const unsigned old = xb_add(&bar[XB_XSUB(b.x)], 1u);
.LBB0_555:
	s_setprio 0
	v_readlane_b32 s69, v255, 17
	s_add_i32 s2, s69, 3
	s_cmp_ge_i32 s2, s77
	s_waitcnt vmcnt(0) lgkmcnt(0)
	s_barrier
	s_cbranch_scc1 .LBB0_568
	v_readlane_b32 s0, v255, 15
	s_cmp_lg_u32 s0, 0
	v_readlane_b32 s68, v255, 18
	v_readlane_b32 s90, v255, 16
	s_cbranch_scc0 .LBB0_569
	s_waitcnt vmcnt(0)
	s_barrier
	s_mov_b64 s[0:1], exec
	v_readlane_b32 s4, v254, 49
	v_readlane_b32 s5, v254, 50
	v_readlane_b32 s86, v255, 6
	s_and_b64 s[4:5], s[0:1], s[4:5]
	v_readlane_b32 s87, v255, 7
	s_mov_b64 exec, s[4:5]
	s_cbranch_execz .LBB0_602
	v_readlane_b32 s3, v254, 41
	s_waitcnt vmcnt(0) expcnt(0) lgkmcnt(0)
	s_nop 0
	v_mov_b32_e32 v1, s3
	ds_read_b32 v3, v1
	v_readlane_b32 s3, v254, 42
	s_waitcnt lgkmcnt(0)
	v_cmp_ne_u32_e32 vcc, 0, v3
	v_mov_b32_e32 v1, s3
	ds_read_b32 v2, v1
	s_cbranch_vccnz .LBB0_573
	s_add_u32 s6, s88, 0x1000
	s_addc_u32 s7, s89, 0
	s_add_u32 s8, s88, 0x1100
	s_addc_u32 s9, s89, 0
	s_add_u32 s10, s88, 0x1200
	s_addc_u32 s11, s89, 0
	s_add_u32 s12, s88, 0x1300
	s_addc_u32 s13, s89, 0
	s_mov_b32 s4, 1
	s_branch .LBB0_561
